# stack without phase-0 change and without relaxed K-loop waits; in-proj epilogue entry wait vmcnt(0)->vmcnt(8)
# baseline (speedup 1.0000x reference)
.LBB0_141:
	s_waitcnt vmcnt(8)
	v_ffbh_u32_e32 v162, v159
	v_min_u32_e32 v162, 32, v162
	v_lshlrev_b64 v[158:159], v162, v[158:159]
	v_min_u32_e32 v158, 1, v158
	v_or_b32_e32 v158, v159, v158
	v_ffbh_u32_e32 v159, v157
	v_min_u32_e32 v159, 32, v159
	v_lshlrev_b64 v[156:157], v159, v[156:157]
	v_min_u32_e32 v156, 1, v156
	v_cvt_f32_u32_e32 v158, v158
	v_or_b32_e32 v156, v157, v156
	v_cvt_f32_u32_e32 v156, v156
	v_sub_u32_e32 v157, 32, v162
	v_ldexp_f32 v157, v158, v157
	v_sub_u32_e32 v158, 32, v159
	v_ldexp_f32 v156, v156, v158
	v_ffbh_u32_e32 v158, v155
	v_min_u32_e32 v158, 32, v158
	v_lshlrev_b64 v[154:155], v158, v[154:155]
	v_min_u32_e32 v154, 1, v154
	v_or_b32_e32 v154, v155, v154
	v_ffbh_u32_e32 v155, v153
	v_min_u32_e32 v155, 32, v155
	v_lshlrev_b64 v[152:153], v155, v[152:153]
	v_min_u32_e32 v152, 1, v152
	v_cvt_f32_u32_e32 v154, v154
	v_or_b32_e32 v152, v153, v152
	v_cvt_f32_u32_e32 v152, v152
	v_sub_u32_e32 v153, 32, v158
	v_ldexp_f32 v153, v154, v153
	v_sub_u32_e32 v154, 32, v155
	s_mov_b32 s2, 0x35800000
	v_ldexp_f32 v152, v152, v154
	v_pk_mul_f32 v[154:155], v[152:153], s[2:3] op_sel_hi:[1,0]
	v_ffbh_u32_e32 v152, v151
	v_min_u32_e32 v152, 32, v152
	v_lshlrev_b64 v[150:151], v152, v[150:151]
	v_min_u32_e32 v150, 1, v150
	v_or_b32_e32 v150, v151, v150
	v_ffbh_u32_e32 v151, v149
	v_min_u32_e32 v151, 32, v151
	v_lshlrev_b64 v[148:149], v151, v[148:149]
	v_min_u32_e32 v148, 1, v148
	v_cvt_f32_u32_e32 v150, v150
	v_or_b32_e32 v148, v149, v148
	v_cvt_f32_u32_e32 v148, v148
	v_sub_u32_e32 v149, 32, v152
	v_ldexp_f32 v149, v150, v149
	v_sub_u32_e32 v150, 32, v151
	v_ldexp_f32 v148, v148, v150
	v_pk_mul_f32 v[152:153], v[148:149], s[2:3] op_sel_hi:[1,0]
	v_ffbh_u32_e32 v148, v143
	v_min_u32_e32 v148, 32, v148
	v_lshlrev_b64 v[142:143], v148, v[142:143]
	v_min_u32_e32 v142, 1, v142
	v_or_b32_e32 v142, v143, v142
	v_ffbh_u32_e32 v143, v141
	v_min_u32_e32 v143, 32, v143
	v_lshlrev_b64 v[140:141], v143, v[140:141]
	v_min_u32_e32 v140, 1, v140
	v_cvt_f32_u32_e32 v142, v142
	v_or_b32_e32 v140, v141, v140
	v_cvt_f32_u32_e32 v140, v140
	v_sub_u32_e32 v141, 32, v148
	v_ldexp_f32 v141, v142, v141
	v_sub_u32_e32 v142, 32, v143
	v_ldexp_f32 v140, v140, v142
	v_lshl_add_u32 v165, s50, 8, v144
	v_lshl_or_b32 v148, s59, 8, v160
	v_mov_b64_e32 v[142:143], s[26:27]
	v_pk_mul_f32 v[156:157], v[156:157], s[2:3] op_sel_hi:[1,0]
	v_pk_mul_f32 v[140:141], v[140:141], s[2:3] op_sel_hi:[1,0]
	v_ashrrev_i32_e32 v149, 31, v148
	v_mad_i64_i32 v[150:151], s[2:3], v165, s18, v[142:143]
	v_lshlrev_b64 v[148:149], 1, v[148:149]
	s_mov_b32 s2, 0x358637bd
	v_lshl_add_u64 v[158:159], v[150:151], 0, v[148:149]
	v_mov_b64_e32 v[150:151], s[2:3]
	s_mov_b32 s4, 0x3a800000
	v_pk_fma_f32 v[156:157], v[156:157], s[4:5], v[150:151] op_sel_hi:[1,0,0]
	v_or_b32_e32 v162, 16, v165
	v_mul_f32_e32 v163, 0x4b800000, v157
	v_cmp_gt_f32_e32 vcc, s96, v157
	s_nop 1
	v_cndmask_b32_e32 v157, v157, v163, vcc
	v_rsq_f32_e32 v157, v157
	v_mad_i64_i32 v[162:163], s[2:3], v162, s18, v[142:143]
	v_lshl_add_u64 v[162:163], v[162:163], 0, v[148:149]
	v_mul_f32_e32 v164, 0x45800000, v157
	v_cndmask_b32_e32 v164, v157, v164, vcc
	v_pk_mul_f32 v[128:129], v[164:165], v[128:129] op_sel_hi:[0,1]
	v_pk_mul_f32 v[126:127], v[164:165], v[126:127] op_sel_hi:[0,1]
	v_pk_mul_f32 v[166:167], v[164:165], v[124:125] op_sel_hi:[0,1]
	v_pk_mul_f32 v[124:125], v[164:165], v[122:123] op_sel_hi:[0,1]
	v_cvt_pk_bf16_f32 v122, v126, v127
	v_cvt_pk_bf16_f32 v123, v128, v129
	v_pk_mul_f32 v[118:119], v[164:165], v[118:119] op_sel_hi:[0,1]
	v_cvt_pk_bf16_f32 v124, v124, v125
	v_cvt_pk_bf16_f32 v125, v166, v167
	flat_store_dwordx4 v[158:159], v[122:125]
	v_cmp_gt_f32_e32 vcc, s96, v156
	v_pk_mul_f32 v[120:121], v[164:165], v[120:121] op_sel_hi:[0,1]
	v_pk_mul_f32 v[122:123], v[164:165], v[116:117] op_sel_hi:[0,1]
	v_pk_mul_f32 v[116:117], v[164:165], v[114:115] op_sel_hi:[0,1]
	v_cvt_pk_bf16_f32 v114, v118, v119
	v_mul_f32_e32 v118, 0x4b800000, v156
	v_cndmask_b32_e32 v118, v156, v118, vcc
	v_rsq_f32_e32 v118, v118
	v_cvt_pk_bf16_f32 v115, v120, v121
	v_cvt_pk_bf16_f32 v116, v116, v117
	v_cvt_pk_bf16_f32 v117, v122, v123
	flat_store_dwordx4 v[158:159], v[114:117] offset:256
	s_nop 1
	v_mul_f32_e32 v114, 0x45800000, v118
	v_cndmask_b32_e32 v114, v118, v114, vcc
	v_pk_mul_f32 v[112:113], v[114:115], v[112:113] op_sel_hi:[0,1]
	v_pk_mul_f32 v[110:111], v[114:115], v[110:111] op_sel_hi:[0,1]
	v_pk_mul_f32 v[116:117], v[114:115], v[108:109] op_sel_hi:[0,1]
	v_pk_mul_f32 v[108:109], v[114:115], v[106:107] op_sel_hi:[0,1]
	v_cvt_pk_bf16_f32 v106, v110, v111
	v_cvt_pk_bf16_f32 v107, v112, v113
	v_cvt_pk_bf16_f32 v108, v108, v109
	v_cvt_pk_bf16_f32 v109, v116, v117
	flat_store_dwordx4 v[162:163], v[106:109]
	v_pk_mul_f32 v[104:105], v[114:115], v[104:105] op_sel_hi:[0,1]
	v_pk_mul_f32 v[102:103], v[114:115], v[102:103] op_sel_hi:[0,1]
	v_pk_mul_f32 v[106:107], v[114:115], v[100:101] op_sel_hi:[0,1]
	v_pk_mul_f32 v[100:101], v[114:115], v[98:99] op_sel_hi:[0,1]
	v_cvt_pk_bf16_f32 v98, v102, v103
	v_cvt_pk_bf16_f32 v99, v104, v105
	v_cvt_pk_bf16_f32 v100, v100, v101
	v_cvt_pk_bf16_f32 v101, v106, v107
	flat_store_dwordx4 v[162:163], v[98:101] offset:256
	v_or_b32_e32 v102, 48, v165
	s_nop 0
	v_pk_fma_f32 v[100:101], v[154:155], s[4:5], v[150:151] op_sel_hi:[1,0,0]
	v_or_b32_e32 v98, 32, v165
	v_mul_f32_e32 v103, 0x4b800000, v101
	v_cmp_gt_f32_e32 vcc, s96, v101
	v_mad_i64_i32 v[98:99], s[2:3], v98, s18, v[142:143]
	s_nop 0
	v_cndmask_b32_e32 v101, v101, v103, vcc
	v_rsq_f32_e32 v101, v101
	v_lshl_add_u64 v[98:99], v[98:99], 0, v[148:149]
	v_mad_i64_i32 v[102:103], s[2:3], v102, s18, v[142:143]
	v_mul_f32_e32 v104, 0x45800000, v101
	v_cndmask_b32_e32 v104, v101, v104, vcc
	v_pk_mul_f32 v[96:97], v[104:105], v[96:97] op_sel_hi:[0,1]
	v_pk_mul_f32 v[94:95], v[104:105], v[94:95] op_sel_hi:[0,1]
	v_pk_mul_f32 v[106:107], v[104:105], v[92:93] op_sel_hi:[0,1]
	v_pk_mul_f32 v[92:93], v[104:105], v[90:91] op_sel_hi:[0,1]
	v_cvt_pk_bf16_f32 v90, v94, v95
	v_cvt_pk_bf16_f32 v91, v96, v97
	v_pk_mul_f32 v[86:87], v[104:105], v[86:87] op_sel_hi:[0,1]
	v_cvt_pk_bf16_f32 v92, v92, v93
	v_cvt_pk_bf16_f32 v93, v106, v107
	flat_store_dwordx4 v[98:99], v[90:93]
	v_cmp_gt_f32_e32 vcc, s96, v100
	v_pk_mul_f32 v[88:89], v[104:105], v[88:89] op_sel_hi:[0,1]
	v_pk_mul_f32 v[90:91], v[104:105], v[84:85] op_sel_hi:[0,1]
	v_pk_mul_f32 v[84:85], v[104:105], v[82:83] op_sel_hi:[0,1]
	v_cvt_pk_bf16_f32 v82, v86, v87
	v_mul_f32_e32 v86, 0x4b800000, v100
	v_cndmask_b32_e32 v86, v100, v86, vcc
	v_rsq_f32_e32 v86, v86
	v_cvt_pk_bf16_f32 v83, v88, v89
	v_cvt_pk_bf16_f32 v84, v84, v85
	v_cvt_pk_bf16_f32 v85, v90, v91
	flat_store_dwordx4 v[98:99], v[82:85] offset:256
	v_lshl_add_u64 v[102:103], v[102:103], 0, v[148:149]
	s_nop 0
	v_mul_f32_e32 v82, 0x45800000, v86
	v_cndmask_b32_e32 v82, v86, v82, vcc
	v_pk_mul_f32 v[80:81], v[82:83], v[80:81] op_sel_hi:[0,1]
	v_pk_mul_f32 v[78:79], v[82:83], v[78:79] op_sel_hi:[0,1]
	v_pk_mul_f32 v[84:85], v[82:83], v[76:77] op_sel_hi:[0,1]
	v_pk_mul_f32 v[76:77], v[82:83], v[74:75] op_sel_hi:[0,1]
	v_cvt_pk_bf16_f32 v74, v78, v79
	v_cvt_pk_bf16_f32 v75, v80, v81
	v_cvt_pk_bf16_f32 v76, v76, v77
	v_cvt_pk_bf16_f32 v77, v84, v85
	flat_store_dwordx4 v[102:103], v[74:77]
	v_pk_mul_f32 v[72:73], v[82:83], v[72:73] op_sel_hi:[0,1]
	v_pk_mul_f32 v[70:71], v[82:83], v[70:71] op_sel_hi:[0,1]
	v_pk_mul_f32 v[74:75], v[82:83], v[68:69] op_sel_hi:[0,1]
	v_pk_mul_f32 v[68:69], v[82:83], v[66:67] op_sel_hi:[0,1]
	v_cvt_pk_bf16_f32 v66, v70, v71
	v_cvt_pk_bf16_f32 v67, v72, v73
	v_cvt_pk_bf16_f32 v68, v68, v69
	v_cvt_pk_bf16_f32 v69, v74, v75
	flat_store_dwordx4 v[102:103], v[66:69] offset:256
	v_add_u32_e32 v70, 0x90, v165
	s_nop 0
	v_pk_fma_f32 v[68:69], v[152:153], s[4:5], v[150:151] op_sel_hi:[1,0,0]
	v_add_u32_e32 v66, 0x80, v165
	v_mul_f32_e32 v71, 0x4b800000, v69
	v_cmp_gt_f32_e32 vcc, s96, v69
	v_mad_i64_i32 v[66:67], s[2:3], v66, s18, v[142:143]
	s_nop 0
	v_cndmask_b32_e32 v69, v69, v71, vcc
	v_rsq_f32_e32 v69, v69
	v_lshl_add_u64 v[66:67], v[66:67], 0, v[148:149]
	v_mad_i64_i32 v[70:71], s[2:3], v70, s18, v[142:143]
	v_mul_f32_e32 v72, 0x45800000, v69
	v_cndmask_b32_e32 v72, v69, v72, vcc
	v_pk_mul_f32 v[64:65], v[72:73], v[64:65] op_sel_hi:[0,1]
	v_pk_mul_f32 v[62:63], v[72:73], v[62:63] op_sel_hi:[0,1]
	v_pk_mul_f32 v[74:75], v[72:73], v[60:61] op_sel_hi:[0,1]
	v_pk_mul_f32 v[60:61], v[72:73], v[58:59] op_sel_hi:[0,1]
	v_cvt_pk_bf16_f32 v58, v62, v63
	v_cvt_pk_bf16_f32 v59, v64, v65
	v_pk_mul_f32 v[54:55], v[72:73], v[54:55] op_sel_hi:[0,1]
	v_cvt_pk_bf16_f32 v60, v60, v61
	v_cvt_pk_bf16_f32 v61, v74, v75
	flat_store_dwordx4 v[66:67], v[58:61]
	v_cmp_gt_f32_e32 vcc, s96, v68
	v_pk_mul_f32 v[56:57], v[72:73], v[56:57] op_sel_hi:[0,1]
	v_pk_mul_f32 v[58:59], v[72:73], v[52:53] op_sel_hi:[0,1]
	v_pk_mul_f32 v[52:53], v[72:73], v[50:51] op_sel_hi:[0,1]
	v_cvt_pk_bf16_f32 v50, v54, v55
	v_mul_f32_e32 v54, 0x4b800000, v68
	v_cndmask_b32_e32 v54, v68, v54, vcc
	v_rsq_f32_e32 v54, v54
	v_cvt_pk_bf16_f32 v51, v56, v57
	v_cvt_pk_bf16_f32 v52, v52, v53
	v_cvt_pk_bf16_f32 v53, v58, v59
	flat_store_dwordx4 v[66:67], v[50:53] offset:256
	v_lshl_add_u64 v[70:71], v[70:71], 0, v[148:149]
	s_nop 0
	v_mul_f32_e32 v50, 0x45800000, v54
	v_cndmask_b32_e32 v50, v54, v50, vcc
	v_pk_mul_f32 v[48:49], v[50:51], v[48:49] op_sel_hi:[0,1]
	v_pk_mul_f32 v[46:47], v[50:51], v[46:47] op_sel_hi:[0,1]
	v_pk_mul_f32 v[52:53], v[50:51], v[44:45] op_sel_hi:[0,1]
	v_pk_mul_f32 v[44:45], v[50:51], v[42:43] op_sel_hi:[0,1]
	v_cvt_pk_bf16_f32 v42, v46, v47
	v_cvt_pk_bf16_f32 v43, v48, v49
	v_cvt_pk_bf16_f32 v44, v44, v45
	v_cvt_pk_bf16_f32 v45, v52, v53
	flat_store_dwordx4 v[70:71], v[42:45]
	v_pk_mul_f32 v[40:41], v[50:51], v[40:41] op_sel_hi:[0,1]
	v_pk_mul_f32 v[38:39], v[50:51], v[38:39] op_sel_hi:[0,1]
	v_pk_mul_f32 v[42:43], v[50:51], v[36:37] op_sel_hi:[0,1]
	v_pk_mul_f32 v[36:37], v[50:51], v[34:35] op_sel_hi:[0,1]
	v_cvt_pk_bf16_f32 v34, v38, v39
	v_cvt_pk_bf16_f32 v35, v40, v41
	v_cvt_pk_bf16_f32 v36, v36, v37
	v_cvt_pk_bf16_f32 v37, v42, v43
	flat_store_dwordx4 v[70:71], v[34:37] offset:256
	v_add_u32_e32 v38, 0xb0, v165
	s_nop 0
	v_pk_fma_f32 v[36:37], v[140:141], s[4:5], v[150:151] op_sel_hi:[1,0,0]
	v_add_u32_e32 v34, 0xa0, v165
	v_mul_f32_e32 v39, 0x4b800000, v37
	v_cmp_gt_f32_e32 vcc, s96, v37
	v_mad_i64_i32 v[34:35], s[2:3], v34, s18, v[142:143]
	s_nop 0
	v_cndmask_b32_e32 v37, v37, v39, vcc
	v_rsq_f32_e32 v37, v37
	v_lshl_add_u64 v[34:35], v[34:35], 0, v[148:149]
	v_mad_i64_i32 v[38:39], s[2:3], v38, s18, v[142:143]
	v_mul_f32_e32 v40, 0x45800000, v37
	v_cndmask_b32_e32 v40, v37, v40, vcc
	v_pk_mul_f32 v[32:33], v[40:41], v[32:33] op_sel_hi:[0,1]
	v_pk_mul_f32 v[30:31], v[40:41], v[30:31] op_sel_hi:[0,1]
	v_pk_mul_f32 v[42:43], v[40:41], v[28:29] op_sel_hi:[0,1]
	v_pk_mul_f32 v[28:29], v[40:41], v[26:27] op_sel_hi:[0,1]
	v_cvt_pk_bf16_f32 v26, v30, v31
	v_cvt_pk_bf16_f32 v27, v32, v33
	v_pk_mul_f32 v[22:23], v[40:41], v[22:23] op_sel_hi:[0,1]
	v_cvt_pk_bf16_f32 v28, v28, v29
	v_cvt_pk_bf16_f32 v29, v42, v43
	flat_store_dwordx4 v[34:35], v[26:29]
	v_cmp_gt_f32_e32 vcc, s96, v36
	v_pk_mul_f32 v[24:25], v[40:41], v[24:25] op_sel_hi:[0,1]
	v_pk_mul_f32 v[26:27], v[40:41], v[20:21] op_sel_hi:[0,1]
	v_pk_mul_f32 v[20:21], v[40:41], v[18:19] op_sel_hi:[0,1]
	v_cvt_pk_bf16_f32 v18, v22, v23
	v_mul_f32_e32 v22, 0x4b800000, v36
	v_cndmask_b32_e32 v22, v36, v22, vcc
	v_rsq_f32_e32 v22, v22
	v_cvt_pk_bf16_f32 v19, v24, v25
	v_cvt_pk_bf16_f32 v20, v20, v21
	v_cvt_pk_bf16_f32 v21, v26, v27
	flat_store_dwordx4 v[34:35], v[18:21] offset:256
	v_lshl_add_u64 v[38:39], v[38:39], 0, v[148:149]
	s_mov_b64 s[2:3], -1
	v_mul_f32_e32 v18, 0x45800000, v22
	v_cndmask_b32_e32 v18, v22, v18, vcc
	v_pk_mul_f32 v[16:17], v[18:19], v[16:17] op_sel_hi:[0,1]
	v_pk_mul_f32 v[14:15], v[18:19], v[14:15] op_sel_hi:[0,1]
	v_pk_mul_f32 v[20:21], v[18:19], v[12:13] op_sel_hi:[0,1]
	v_pk_mul_f32 v[12:13], v[18:19], v[10:11] op_sel_hi:[0,1]
	v_cvt_pk_bf16_f32 v10, v14, v15
	v_cvt_pk_bf16_f32 v11, v16, v17
	v_cvt_pk_bf16_f32 v12, v12, v13
	v_cvt_pk_bf16_f32 v13, v20, v21
	flat_store_dwordx4 v[38:39], v[10:13]
	s_andn2_b64 vcc, exec, s[38:39]
	v_pk_mul_f32 v[8:9], v[18:19], v[8:9] op_sel_hi:[0,1]
	v_pk_mul_f32 v[10:11], v[18:19], v[4:5] op_sel_hi:[0,1]
	v_pk_mul_f32 v[4:5], v[18:19], v[2:3] op_sel_hi:[0,1]
	v_pk_mul_f32 v[6:7], v[18:19], v[6:7] op_sel_hi:[0,1]
	v_cvt_pk_bf16_f32 v2, v6, v7
	v_cvt_pk_bf16_f32 v3, v8, v9
	v_cvt_pk_bf16_f32 v4, v4, v5
	v_cvt_pk_bf16_f32 v5, v10, v11
	flat_store_dwordx4 v[38:39], v[2:5] offset:256
	s_cbranch_vccnz .LBB0_134
	s_nop 0
	v_lshl_add_u32 v2, s44, 8, v144
	v_ashrrev_i32_e32 v3, 31, v2
	v_lshl_add_u64 v[2:3], v[2:3], 3, s[34:35]
	flat_load_dwordx2 v[158:159], v[2:3]
	flat_load_dwordx2 v[156:157], v[2:3] offset:128
	flat_load_dwordx2 v[154:155], v[2:3] offset:256
	flat_load_dwordx2 v[152:153], v[2:3] offset:384
	flat_load_dwordx2 v[150:151], v[2:3] offset:1024
	flat_load_dwordx2 v[148:149], v[2:3] offset:1152
	flat_load_dwordx2 v[142:143], v[2:3] offset:1280
	flat_load_dwordx2 v[140:141], v[2:3] offset:1408
	s_andn2_b64 vcc, exec, s[20:21]
	s_cbranch_vccnz .LBB0_133
	s_barrier
	s_branch .LBB0_133
